# v14 + one static s_setprio 1 for waves 4-7 during the attention phases (reset afterwards)
# baseline (speedup 1.0000x reference)
.LBB0_518:
	v_readlane_b32 s0, v255, 29
	s_or_b32 s2, s0, 2
	v_readlane_b32 s4, v253, 2
	v_readlane_b32 s5, v253, 3
	s_cmp_le_i32 s4, s2
	s_cselect_b64 s[0:1], -1, 0
	s_cmp_lt_i32 s2, s5
	s_cselect_b64 s[2:3], -1, 0
	s_and_b64 s[0:1], s[0:1], s[2:3]
	s_andn2_b64 vcc, exec, s[0:1]
	v_readlane_b32 s6, v253, 4
	v_readlane_b32 s7, v253, 5
	s_cbranch_vccnz .LBB0_739
	s_mov_b32 s0, -1
	s_mov_b32 s4, s85
	s_waitcnt vmcnt(0)
	v_mbcnt_lo_u32_b32 v0, s0, 0
	v_mbcnt_hi_u32_b32 v60, s0, v0
	s_cmp_lt_u32 s90, 0x100
	s_cbranch_scc1 .Lprio_attnC
	s_setprio 1
.Lprio_attnC:
	s_mov_b32 s0, s97
	s_mov_b64 s[2:3], s[48:49]
	s_load_dwordx2 s[6:7], s[2:3], 0x118
	s_load_dwordx2 s[0:1], s[2:3], 0xf0
	s_waitcnt lgkmcnt(0)
	s_add_u32 s22, s6, 0x12c80000
	s_addc_u32 s23, s7, 0
	s_add_u32 s56, s6, 0x16d00000
	s_addc_u32 s57, s7, 0
	s_add_u32 s58, s6, 0x1ad80000
	s_addc_u32 s59, s7, 0
	s_add_u32 s60, s6, 0x1ee00000
	s_addc_u32 s61, s7, 0
	v_readlane_b32 s6, v253, 12
	v_readlane_b32 s7, v253, 13
	s_andn2_b64 vcc, exec, s[6:7]
	s_cbranch_vccnz .LBB0_551
	v_readlane_b32 s6, v254, 34
	v_readlane_b32 s7, v254, 35
	v_and_b32_e32 v61, 15, v60
	s_andn2_b64 vcc, exec, s[6:7]
	s_cbranch_vccnz .LBB0_546
	v_readlane_b32 s24, v254, 46
	v_readlane_b32 s25, v254, 47
	s_add_u32 s5, s58, s24
	v_readlane_b32 s20, v254, 30
	s_addc_u32 s7, s59, s25
	s_lshl_b32 s18, s20, 1
	s_add_u32 s6, s5, s18
	s_addc_u32 s7, s7, 0
	s_load_dwordx4 s[12:15], s[2:3], 0x30
	s_add_u32 s2, s56, s24
	s_addc_u32 s3, s57, s25
	s_add_u32 s10, s2, s18
	s_addc_u32 s11, s3, 0
	v_readlane_b32 s26, v254, 48
	v_readlane_b32 s27, v254, 49
	s_waitcnt lgkmcnt(0)
	s_add_u32 s2, s14, s26
	s_addc_u32 s3, s15, s27
	s_lshl_b32 s5, s20, 2
	s_add_u32 s14, s2, s5
	s_addc_u32 s15, s3, 0
	s_add_u32 s2, s12, s26
	s_addc_u32 s3, s13, s27
	s_add_u32 s12, s2, s5
	s_addc_u32 s13, s3, 0
	s_add_u32 s2, s22, s24
	v_ashrrev_i32_e32 v6, 4, v60
	s_addc_u32 s3, s23, s25
	v_lshlrev_b32_e32 v0, 3, v6
	s_add_u32 s2, s2, s18
	v_ashrrev_i32_e32 v1, 31, v0
	s_addc_u32 s3, s3, 0
	v_lshlrev_b32_e32 v128, 11, v61
	v_lshl_add_u64 v[2:3], s[2:3], 0, v[128:129]
	v_lshlrev_b64 v[4:5], 1, v[0:1]
	v_lshl_add_u64 v[2:3], v[2:3], 0, v[4:5]
	global_load_dwordx4 v[20:23], v[2:3], off offset:64
	global_load_dwordx4 v[24:27], v[2:3], off
	v_lshlrev_b32_e32 v128, 2, v61
	v_lshlrev_b32_e32 v62, 2, v6
	s_cmp_lg_u64 s[0:1], 0
	v_lshl_add_u64 v[34:35], s[14:15], 0, v[128:129]
	v_lshlrev_b32_e32 v128, 1, v61
	v_readlane_b32 s5, v254, 45
	v_mov_b32_e32 v64, 0
	s_cselect_b64 s[2:3], -1, 0
	v_lshl_add_u64 v[32:33], s[10:11], 0, v[4:5]
	v_lshl_add_u64 v[36:37], v[0:1], 2, s[12:13]
	v_lshl_add_u64 v[38:39], s[6:7], 0, v[128:129]
	v_sub_u32_e32 v63, s5, v62
	v_mov_b32_e32 v96, 0xf149f2ca
	s_mov_b32 s5, s90
	v_mov_b32_e32 v28, 0
	v_mov_b32_e32 v29, v64
	v_mov_b32_e32 v30, v64
	v_mov_b32_e32 v31, v64
	v_mov_b32_e32 v16, 0
	v_mov_b32_e32 v17, v64
	v_mov_b32_e32 v18, v64
	v_mov_b32_e32 v19, v64
	v_mov_b32_e32 v12, 0
	v_mov_b32_e32 v13, v64
	v_mov_b32_e32 v14, v64
	v_mov_b32_e32 v15, v64
	v_mov_b32_e32 v8, 0
	v_mov_b32_e32 v9, v64
	v_mov_b32_e32 v10, v64
	v_mov_b32_e32 v11, v64
	v_readlane_b32 s6, v254, 33
	v_readlane_b32 s7, v254, 36

.LBB0_739:
	v_readlane_b32 s0, v255, 29
	s_or_b32 s2, s0, 3
	v_readlane_b32 s4, v253, 2
	v_readlane_b32 s5, v253, 3
	s_cmp_le_i32 s4, s2
	s_cselect_b64 s[0:1], -1, 0
	s_cmp_lt_i32 s2, s5
	s_cselect_b64 s[2:3], -1, 0
	s_and_b64 s[2:3], s[0:1], s[2:3]
	s_andn2_b64 vcc, exec, s[2:3]
	s_mov_b64 s[2:3], 0
	v_writelane_b32 v255, s2, 30
	s_mov_b64 s[0:1], 0
	v_readlane_b32 s6, v253, 4
	v_writelane_b32 v255, s3, 31
	v_readlane_b32 s7, v253, 5
	s_cbranch_vccnz .LBB0_844
	s_mov_b32 s2, -1
	s_mov_b32 s4, s85
	s_waitcnt vmcnt(0)
	v_mbcnt_lo_u32_b32 v0, s2, 0
	v_mbcnt_hi_u32_b32 v146, s2, v0
	s_setprio 0
	s_mov_b32 s5, s97
	s_cmpk_lt_i32 s5, 0x200
	v_add_u32_e32 v145, s90, v146
	s_mov_b64 s[2:3], s[48:49]
	v_readfirstlane_b32 s33, v145
	s_movk_i32 s36, 0x400
	s_cselect_b64 s[22:23], -1, 0
	s_cmpk_gt_i32 s5, 0x1ff
	s_cbranch_scc1 .LBB0_746
	s_ashr_i32 s6, s5, 31
	s_lshr_b32 s6, s6, 29
	s_add_i32 s6, s5, s6
	s_and_b32 s7, s6, -8
	s_sub_i32 s7, s5, s7
	s_cmp_gt_i32 s7, -1
	s_mov_b64 s[10:11], -1
	s_cbranch_scc0 .LBB0_743
	s_lshl_b32 s12, s7, 6
	s_mov_b64 s[10:11], 0

.LBB0_1895:
	v_readlane_b32 s0, v255, 29
	s_or_b32 s2, s0, 2
	v_readlane_b32 s4, v253, 2
	v_readlane_b32 s5, v253, 3
	s_cmp_le_i32 s4, s2
	s_cselect_b64 s[0:1], -1, 0
	s_cmp_lt_i32 s2, s5
	s_cselect_b64 s[2:3], -1, 0
	s_and_b64 s[0:1], s[0:1], s[2:3]
	s_andn2_b64 vcc, exec, s[0:1]
	v_readlane_b32 s6, v253, 4
	v_readlane_b32 s7, v253, 5
	s_cbranch_vccnz .LBB0_2107
	s_mov_b32 s0, -1
	s_mov_b32 s1, s85
	s_waitcnt vmcnt(0)
	v_mbcnt_lo_u32_b32 v0, s0, 0
	v_mbcnt_hi_u32_b32 v2, s0, v0
	s_cmp_lt_u32 s90, 0x100
	s_cbranch_scc1 .Lprio_attnA
	s_setprio 1
.Lprio_attnA:
	s_mov_b32 s0, s97
	s_mov_b64 s[46:47], s[48:49]
	s_load_dwordx2 s[2:3], s[46:47], 0x70
	v_readlane_b32 s4, v255, 27
	v_readlane_b32 s5, v255, 28
	s_and_b64 s[4:5], s[4:5], exec
	s_cselect_b32 s0, 0x400, 0
	s_waitcnt lgkmcnt(0)
	s_add_u32 s2, s2, s0
	s_addc_u32 s3, s3, 0
	v_ashrrev_i32_e32 v3, 31, v2
	v_lshl_add_u64 v[4:5], v[2:3], 2, s[2:3]
	v_add_u32_e32 v0, s90, v2
	global_load_dword v1, v[4:5], off
	global_load_dword v2, v[4:5], off offset:256
	s_add_i32 s2, s1, 0x3ff
	s_xor_b32 s0, s2, s1
	s_abs_i32 s1, s1
	s_sub_i32 s3, 0, s1
	s_abs_i32 s2, s2
	s_ashr_i32 s0, s0, 31
	s_waitcnt vmcnt(0)
	v_mul_f32_e32 v3, v1, v2
	ds_swizzle_b32 v3, v3 offset:swizzle(SWAP,1)
	s_waitcnt lgkmcnt(0)
	v_fmac_f32_e32 v3, v1, v2
	ds_swizzle_b32 v1, v3 offset:swizzle(SWAP,2)
	s_waitcnt lgkmcnt(0)
	v_add_f32_e32 v1, v3, v1
	global_load_dword v3, v[4:5], off offset:512
	s_nop 0
	global_load_dword v4, v[4:5], off offset:768
	ds_swizzle_b32 v2, v1 offset:swizzle(SWAP,4)
	s_waitcnt vmcnt(0) lgkmcnt(0)
	s_waitcnt lgkmcnt(0)
	s_barrier
	v_add_f32_e32 v1, v1, v2
	ds_swizzle_b32 v2, v1 offset:swizzle(SWAP,8)
	s_waitcnt lgkmcnt(0)
	v_add_f32_e32 v1, v1, v2
	ds_swizzle_b32 v2, v1 offset:swizzle(SWAP,16)
	s_waitcnt lgkmcnt(0)
	v_add_f32_e32 v1, v1, v2
	v_mov_b32_e32 v2, v1
	s_nop 1
	v_permlane32_swap_b32_e32 v1, v2
	s_waitcnt vmcnt(0)
	v_mul_f32_e32 v5, v3, v4
	ds_swizzle_b32 v5, v5 offset:swizzle(SWAP,1)
	s_waitcnt lgkmcnt(0)
	v_fmac_f32_e32 v5, v3, v4
	ds_swizzle_b32 v3, v5 offset:swizzle(SWAP,2)
	s_waitcnt lgkmcnt(0)
	v_add_f32_e32 v3, v5, v3
	v_cvt_f32_u32_e32 v5, s1
	ds_swizzle_b32 v4, v3 offset:swizzle(SWAP,4)
	v_rcp_iflag_f32_e32 v5, v5
	s_waitcnt lgkmcnt(0)
	v_add_f32_e32 v3, v3, v4
	ds_swizzle_b32 v4, v3 offset:swizzle(SWAP,8)
	v_mul_f32_e32 v5, 0x4f7ffffe, v5
	v_cvt_u32_f32_e32 v5, v5
	s_waitcnt lgkmcnt(0)
	v_add_f32_e32 v3, v3, v4
	v_readfirstlane_b32 s4, v5
	s_mul_i32 s3, s3, s4
	s_mul_hi_u32 s3, s4, s3
	s_add_i32 s4, s4, s3
	s_mul_hi_u32 s3, s2, s4
	s_mul_i32 s4, s3, s1
	s_sub_i32 s2, s2, s4
	s_add_i32 s4, s3, 1
	s_sub_i32 s5, s2, s1
	ds_swizzle_b32 v4, v3 offset:swizzle(SWAP,16)
	s_cmp_ge_u32 s2, s1
	s_cselect_b32 s3, s4, s3
	s_cselect_b32 s2, s5, s2
	s_add_i32 s4, s3, 1
	s_cmp_ge_u32 s2, s1
	s_cselect_b32 s1, s4, s3
	s_waitcnt lgkmcnt(0)
	v_add_f32_e32 v3, v3, v4
	s_xor_b32 s1, s1, s0
	v_mov_b32_e32 v4, v3
	s_sub_i32 s62, s1, s0
	s_nop 0
	v_permlane32_swap_b32_e32 v3, v4
	s_cmp_lt_i32 s62, 0
	s_cbranch_scc1 .LBB0_2057
	s_load_dwordx2 s[0:1], s[46:47], 0x118
	v_readlane_b32 s10, v255, 27
	v_readlane_b32 s11, v255, 28
	v_and_b32_e32 v236, 63, v0
	v_add_f32_e32 v0, v1, v2
	s_waitcnt lgkmcnt(0)
	s_add_u32 s63, s0, 0x12c80000
	s_addc_u32 s64, s1, 0
	s_add_u32 s65, s0, 0x16d00000
	s_addc_u32 s70, s1, 0
	s_add_u32 s71, s0, 0x1ad80000
	s_addc_u32 s72, s1, 0
	s_add_u32 s73, s0, 0x1ee00000
	s_addc_u32 s67, s1, 0
	v_cndmask_b32_e64 v5, 0, 1, s[10:11]
	s_add_u32 s12, s0, 0x43280000
	v_lshlrev_b32_e32 v5, 2, v5
	s_addc_u32 s13, s1, 0
	v_readfirstlane_b32 s2, v5
	s_add_u32 s14, s0, 0x45280000
	s_load_dword s4, s[46:47], s2 offset:0x130
	s_nop 0
	s_load_dwordx2 s[2:3], s[46:47], 0x78
	s_addc_u32 s15, s1, 0
	s_add_u32 s50, s0, 0x22e80000
	s_addc_u32 s51, s1, 0
	s_and_b64 s[0:1], s[10:11], exec
	s_cselect_b32 s0, 0x200, 0
	s_waitcnt lgkmcnt(0)
	s_add_u32 s60, s2, s0
	s_addc_u32 s61, s3, 0
	s_add_i32 s0, s62, 1
	s_not_b32 s1, s62
	s_max_i32 s0, s0, s1
	v_cvt_f32_u32_e32 v5, s0
	v_mul_f32_e32 v2, 0x3fb8aa3b, v0
	s_mov_b32 s6, 0x3fb8aa3b
	s_sub_i32 s1, 0, s0
	v_rcp_iflag_f32_e32 v5, v5
	v_readlane_b32 s3, v254, 53
	v_sub_f32_e64 v208, 1.0, s4
	s_mov_b32 s85, 0
	v_mul_f32_e32 v1, 0x4f7ffffe, v5
	v_cvt_u32_f32_e32 v1, v1
	v_fma_f32 v5, v0, s6, -v2
	v_fmac_f32_e32 v5, 0x32a5705f, v0
	v_mov_b32_e32 v209, v208
	v_readfirstlane_b32 s2, v1
	s_mul_i32 s1, s1, s2
	v_rndne_f32_e32 v1, v2
	s_mul_hi_u32 s1, s2, s1
	v_sub_f32_e32 v2, v2, v1
	s_add_i32 s2, s2, s1
	v_add_f32_e32 v2, v2, v5
	s_mul_hi_u32 s1, s3, s2
	v_exp_f32_e32 v2, v2
	v_cvt_i32_f32_e32 v1, v1
	s_mul_i32 s1, s1, s0
	s_sub_i32 s1, s3, s1
	s_sub_i32 s2, s1, s0
	s_cmp_ge_u32 s1, s0
	v_ldexp_f32 v1, v2, v1
	v_add_f32_e32 v2, v3, v4
	s_cselect_b32 s1, s2, s1
	v_mul_f32_e32 v3, 0x3fb8aa3b, v2
	s_sub_i32 s2, s1, s0
	v_fma_f32 v4, v2, s6, -v3
	v_rndne_f32_e32 v5, v3
	s_cmp_ge_u32 s1, s0
	v_fmac_f32_e32 v4, 0x32a5705f, v2
	v_sub_f32_e32 v3, v3, v5
	s_cselect_b32 s0, s2, s1
	v_readlane_b32 s1, v254, 52
	v_add_f32_e32 v3, v3, v4
	s_xor_b32 s0, s0, s1
	v_exp_f32_e32 v3, v3
	v_cvt_i32_f32_e32 v4, v5
	s_sub_i32 s86, s0, s1
	s_mov_b32 s0, 0xc2ce8ed0
	v_cmp_ngt_f32_e32 vcc, s0, v0
	s_mov_b32 s1, 0x42b17218
	v_mov_b32_e32 v5, 0x7f800000
	v_cndmask_b32_e32 v1, 0, v1, vcc
	v_cmp_nlt_f32_e32 vcc, s1, v0
	s_nop 1
	v_cndmask_b32_e32 v0, v5, v1, vcc
	v_ldexp_f32 v1, v3, v4
	v_cmp_ngt_f32_e32 vcc, s0, v2
	s_nop 1
	v_cndmask_b32_e32 v1, 0, v1, vcc
	v_cmp_nlt_f32_e32 vcc, s1, v2
	s_and_b64 s[0:1], s[10:11], exec
	s_cselect_b32 s87, 16, 0
	v_cndmask_b32_e32 v1, v5, v1, vcc
	v_sub_f32_e32 v0, v0, v1
	v_add_f32_e32 v206, s4, v0
	v_mov_b32_e32 v207, v206
	s_branch .LBB0_1900

.LBB0_2107:
	v_readlane_b32 s0, v255, 29
	s_or_b32 s2, s0, 3
	v_readlane_b32 s4, v253, 2
	v_readlane_b32 s5, v253, 3
	s_cmp_le_i32 s4, s2
	s_cselect_b64 s[0:1], -1, 0
	s_cmp_lt_i32 s2, s5
	s_cselect_b64 s[2:3], -1, 0
	s_and_b64 s[0:1], s[0:1], s[2:3]
	s_andn2_b64 vcc, exec, s[0:1]
	v_readlane_b32 s6, v253, 4
	v_readlane_b32 s7, v253, 5
	s_cbranch_vccnz .LBB0_2161
	s_mov_b32 s0, -1
	s_setprio 0
	s_mov_b32 s1, s97
	s_waitcnt vmcnt(0)
	v_mbcnt_lo_u32_b32 v0, s0, 0
	v_mbcnt_hi_u32_b32 v2, s0, v0
	s_mov_b32 s0, s85
	s_mov_b64 s[0:1], s[48:49]
	s_load_dwordx2 s[2:3], s[0:1], 0x70
	v_readlane_b32 s4, v255, 27
	v_readlane_b32 s5, v255, 28
	s_and_b64 s[4:5], s[4:5], exec
	s_cselect_b32 s4, 0x400, 0
	s_waitcnt lgkmcnt(0)
	s_add_u32 s2, s2, s4
	s_addc_u32 s3, s3, 0
	v_ashrrev_i32_e32 v3, 31, v2
	v_lshl_add_u64 v[4:5], v[2:3], 2, s[2:3]
	global_load_dword v0, v[4:5], off
	global_load_dword v1, v[4:5], off offset:256
	v_readlane_b32 s2, v254, 22
	v_readlane_b32 s3, v254, 23
	s_andn2_b64 vcc, exec, s[2:3]
	s_mov_b32 s14, 0xf149f2ca
	s_waitcnt vmcnt(0)
	v_mul_f32_e32 v3, v0, v1
	ds_swizzle_b32 v3, v3 offset:swizzle(SWAP,1)
	s_waitcnt lgkmcnt(0)
	v_fmac_f32_e32 v3, v0, v1
	ds_swizzle_b32 v0, v3 offset:swizzle(SWAP,2)
	s_waitcnt lgkmcnt(0)
	v_add_f32_e32 v0, v3, v0
	global_load_dword v3, v[4:5], off offset:512
	s_nop 0
	global_load_dword v4, v[4:5], off offset:768
	ds_swizzle_b32 v1, v0 offset:swizzle(SWAP,4)
	s_waitcnt lgkmcnt(0)
	v_add_f32_e32 v0, v0, v1
	ds_swizzle_b32 v1, v0 offset:swizzle(SWAP,8)
	s_waitcnt lgkmcnt(0)
	v_add_f32_e32 v0, v0, v1
	ds_swizzle_b32 v1, v0 offset:swizzle(SWAP,16)
	s_waitcnt lgkmcnt(0)
	v_add_f32_e32 v0, v0, v1
	v_mov_b32_e32 v1, v0
	s_nop 1
	v_permlane32_swap_b32_e32 v0, v1
	s_waitcnt vmcnt(0)
	v_mul_f32_e32 v5, v3, v4
	ds_swizzle_b32 v5, v5 offset:swizzle(SWAP,1)
	s_waitcnt lgkmcnt(0)
	v_fmac_f32_e32 v5, v3, v4
	ds_swizzle_b32 v3, v5 offset:swizzle(SWAP,2)
	s_waitcnt lgkmcnt(0)
	v_add_f32_e32 v3, v5, v3
	ds_swizzle_b32 v4, v3 offset:swizzle(SWAP,4)
	s_waitcnt lgkmcnt(0)
	v_add_f32_e32 v3, v3, v4
	ds_swizzle_b32 v4, v3 offset:swizzle(SWAP,8)
	s_waitcnt lgkmcnt(0)
	v_add_f32_e32 v3, v3, v4
	ds_swizzle_b32 v4, v3 offset:swizzle(SWAP,16)
	s_waitcnt lgkmcnt(0)
	v_add_f32_e32 v3, v3, v4
	v_mov_b32_e32 v4, v3
	s_nop 1
	v_permlane32_swap_b32_e32 v3, v4
	s_cbranch_vccnz .LBB0_2111
	v_readlane_b32 s6, v255, 27
	v_readlane_b32 s7, v255, 28
	v_add_f32_e32 v0, v0, v1
	v_mul_f32_e32 v1, 0x3fb8aa3b, v0
	v_cndmask_b32_e64 v5, 0, 1, s[6:7]
	v_lshlrev_b32_e32 v5, 2, v5
	v_rndne_f32_e32 v6, v1
	v_readfirstlane_b32 s4, v5
	v_fma_f32 v5, v0, s46, -v1
	v_fmac_f32_e32 v5, 0x32a5705f, v0
	v_sub_f32_e32 v1, v1, v6
	s_load_dwordx2 s[2:3], s[0:1], 0x118
	v_add_f32_e32 v1, v1, v5
	v_exp_f32_e32 v1, v1
	v_cvt_i32_f32_e32 v5, v6
	v_add_f32_e32 v3, v3, v4
	s_load_dword s10, s[0:1], s4 offset:0x130
	s_nop 0
	s_load_dwordx2 s[0:1], s[0:1], 0x78
	v_mul_f32_e32 v4, 0x3fb8aa3b, v3
	s_waitcnt lgkmcnt(0)
	s_add_u32 s4, s2, 0x45280000
	v_ldexp_f32 v1, v1, v5
	v_fma_f32 v5, v3, s46, -v4
	v_rndne_f32_e32 v6, v4
	s_addc_u32 s5, s3, 0
	v_fmac_f32_e32 v5, 0x32a5705f, v3
	v_sub_f32_e32 v4, v4, v6
	s_and_b64 s[6:7], s[6:7], exec
	v_add_f32_e32 v4, v4, v5
	s_cselect_b32 s6, 0x200, 0
	v_exp_f32_e32 v4, v4
	v_cvt_i32_f32_e32 v5, v6
	s_add_u32 s0, s0, s6
	s_mov_b32 s6, 0xc2ce8ed0
	v_cmp_ngt_f32_e32 vcc, s6, v0
	s_mov_b32 s7, 0x42b17218
	v_mov_b32_e32 v6, 0x7f800000
	v_cndmask_b32_e32 v1, 0, v1, vcc
	v_cmp_nlt_f32_e32 vcc, s7, v0
	s_addc_u32 s1, s1, 0
	v_sub_f32_e64 v76, 1.0, s10
	v_cndmask_b32_e32 v0, v6, v1, vcc
	v_ldexp_f32 v1, v4, v5
	v_cmp_ngt_f32_e32 vcc, s6, v3
	s_nop 1
	v_cndmask_b32_e32 v1, 0, v1, vcc
	v_cmp_nlt_f32_e32 vcc, s7, v3
	s_mov_b64 s[6:7], 0x43280000
	s_nop 0
	v_cndmask_b32_e32 v1, v6, v1, vcc
	v_lshlrev_b32_e32 v6, 1, v2
	v_ashrrev_i32_e32 v7, 31, v6
	v_lshlrev_b64 v[4:5], 2, v[6:7]
	v_lshl_add_u64 v[2:3], s[2:3], 0, v[4:5]
	v_lshl_add_u64 v[4:5], s[0:1], 0, v[4:5]
	v_readlane_b32 s0, v254, 51
	s_add_u32 s0, s2, s0
	s_addc_u32 s1, s3, 0
	v_sub_f32_e32 v0, v0, v1
	v_lshl_add_u64 v[6:7], v[6:7], 1, s[0:1]
	s_mov_b64 s[0:1], 0x1ee00000
	v_add_f32_e32 v0, s10, v0
	v_lshl_add_u64 v[6:7], v[6:7], 0, s[0:1]
	v_readlane_b32 s0, v255, 7
	v_lshl_add_u64 v[2:3], v[2:3], 0, s[6:7]
	v_readlane_b32 s7, v254, 50
	v_mov_b32_e32 v1, v0
	s_mov_b32 s6, s0
	v_readlane_b32 s1, v255, 8
